# S5 pass 1 (phase C) recurrence: bu rows read up front + scalar f32 state update, on top of the pass 2 version
# speedup vs baseline: 1.0077x; 1.0011x over previous
; DI u16 f2bf(float x) { return (u16)(pk2(x, 0.f) & 0xffffu); }
; DI f32x4 mfma16(bf16x8 a, bf16x8 b, f32x4 c) { return __builtin_amdgcn_mfma_f32_16x16x32_bf16(a, b, c, 0, 0, 0); }
; template <bool OUT>
; DI void s5_item(int wv0, PP p, int item, unsigned char* smem) {
;     ...
;   for (int sub = 0; sub < 4; ++sub) {
;     const bf16x8 ua = uall[sub];
; #pragma unroll
;     for (int nt = 0; nt < 8; ++nt) {
;       const f32x4 a = mfma16(ua, bb[nt], f32x4{0.f, 0.f, 0.f, 0.f});
; #pragma unroll
;       for (int j = 0; j < 4; ++j) sBU[(4 * fq + j) * 132 + 16 * nt + fr] = a[j];
;     }
;     __syncthreads();
; #pragma unroll 4
;     for (int t = 0; t < 16; ++t) {
;       const float bur = sBU[t * 132 + lane], bui = sBU[t * 132 + 64 + lane];
;       const float nr = lbr * hr - lbi * hi + bur;
;       const float nim = lbr * hi + lbi * hr + bui;
;       hr = nr;
;       hi = nim;
;       if (OUT) {
;         sH[t * 136 + lane] = f2bf(hr);
;         sH[t * 136 + 64 + lane] = f2bf(hi);
;       }
;     }
.LBB0_441:
	v_mov_b32_e32 v117, v49
	v_add_u32_e32 v118, 1056, v49
	v_add_u32_e32 v119, 2112, v49
	v_add_u32_e32 v120, 3168, v49
	v_add_u32_e32 v121, 4224, v49
	v_add_u32_e32 v122, 5280, v49
	v_add_u32_e32 v123, 6336, v49
	v_add_u32_e32 v124, 7392, v49
	ds_read2st64_b32 v[152:153], v117 offset1:1
	ds_read2_b32 v[154:155], v117 offset0:132 offset1:196
	ds_read2st64_b32 v[156:157], v118 offset1:1
	ds_read2_b32 v[158:159], v118 offset0:132 offset1:196
	ds_read2st64_b32 v[160:161], v119 offset1:1
	ds_read2_b32 v[162:163], v119 offset0:132 offset1:196
	ds_read2st64_b32 v[164:165], v120 offset1:1
	ds_read2_b32 v[166:167], v120 offset0:132 offset1:196
	ds_read2st64_b32 v[168:169], v121 offset1:1
	ds_read2_b32 v[170:171], v121 offset0:132 offset1:196
	ds_read2st64_b32 v[172:173], v122 offset1:1
	ds_read2_b32 v[174:175], v122 offset0:132 offset1:196
	ds_read2st64_b32 v[176:177], v123 offset1:1
	ds_read2_b32 v[178:179], v123 offset0:132 offset1:196
	ds_read2st64_b32 v[180:181], v124 offset1:1
	ds_read2_b32 v[182:183], v124 offset0:132 offset1:196
	s_waitcnt lgkmcnt(0)
	v_mul_f32_e32 v184, v44, v52
	v_mul_f32_e32 v185, v45, v52
	v_fma_f32 v186, v50, v46, -v184
	v_fma_f32 v187, v51, v46, v185
	v_add_f32_e32 v192, v186, v152
	v_add_f32_e32 v193, v187, v153
	v_mul_f32_e32 v184, v44, v193
	v_mul_f32_e32 v185, v45, v193
	v_fma_f32 v186, v50, v192, -v184
	v_fma_f32 v187, v51, v192, v185
	v_add_f32_e32 v46, v186, v154
	v_add_f32_e32 v47, v187, v155
	v_mul_f32_e32 v184, v44, v47
	v_mul_f32_e32 v185, v45, v47
	v_fma_f32 v186, v50, v46, -v184
	v_fma_f32 v187, v51, v46, v185
	v_add_f32_e32 v192, v186, v156
	v_add_f32_e32 v193, v187, v157
	v_mul_f32_e32 v184, v44, v193
	v_mul_f32_e32 v185, v45, v193
	v_fma_f32 v186, v50, v192, -v184
	v_fma_f32 v187, v51, v192, v185
	v_add_f32_e32 v46, v186, v158
	v_add_f32_e32 v47, v187, v159
	v_mul_f32_e32 v184, v44, v47
	v_mul_f32_e32 v185, v45, v47
	v_fma_f32 v186, v50, v46, -v184
	v_fma_f32 v187, v51, v46, v185
	v_add_f32_e32 v192, v186, v160
	v_add_f32_e32 v193, v187, v161
	v_mul_f32_e32 v184, v44, v193
	v_mul_f32_e32 v185, v45, v193
	v_fma_f32 v186, v50, v192, -v184
	v_fma_f32 v187, v51, v192, v185
	v_add_f32_e32 v46, v186, v162
	v_add_f32_e32 v47, v187, v163
	v_mul_f32_e32 v184, v44, v47
	v_mul_f32_e32 v185, v45, v47
	v_fma_f32 v186, v50, v46, -v184
	v_fma_f32 v187, v51, v46, v185
	v_add_f32_e32 v192, v186, v164
	v_add_f32_e32 v193, v187, v165
	v_mul_f32_e32 v184, v44, v193
	v_mul_f32_e32 v185, v45, v193
	v_fma_f32 v186, v50, v192, -v184
	v_fma_f32 v187, v51, v192, v185
	v_add_f32_e32 v46, v186, v166
	v_add_f32_e32 v47, v187, v167
	v_mul_f32_e32 v184, v44, v47
	v_mul_f32_e32 v185, v45, v47
	v_fma_f32 v186, v50, v46, -v184
	v_fma_f32 v187, v51, v46, v185
	v_add_f32_e32 v192, v186, v168
	v_add_f32_e32 v193, v187, v169
	v_mul_f32_e32 v184, v44, v193
	v_mul_f32_e32 v185, v45, v193
	v_fma_f32 v186, v50, v192, -v184
	v_fma_f32 v187, v51, v192, v185
	v_add_f32_e32 v46, v186, v170
	v_add_f32_e32 v47, v187, v171
	v_mul_f32_e32 v184, v44, v47
	v_mul_f32_e32 v185, v45, v47
	v_fma_f32 v186, v50, v46, -v184
	v_fma_f32 v187, v51, v46, v185
	v_add_f32_e32 v192, v186, v172
	v_add_f32_e32 v193, v187, v173
	v_mul_f32_e32 v184, v44, v193
	v_mul_f32_e32 v185, v45, v193
	v_fma_f32 v186, v50, v192, -v184
	v_fma_f32 v187, v51, v192, v185
	v_add_f32_e32 v46, v186, v174
	v_add_f32_e32 v47, v187, v175
	v_mul_f32_e32 v184, v44, v47
	v_mul_f32_e32 v185, v45, v47
	v_fma_f32 v186, v50, v46, -v184
	v_fma_f32 v187, v51, v46, v185
	v_add_f32_e32 v192, v186, v176
	v_add_f32_e32 v193, v187, v177
	v_mul_f32_e32 v184, v44, v193
	v_mul_f32_e32 v185, v45, v193
	v_fma_f32 v186, v50, v192, -v184
	v_fma_f32 v187, v51, v192, v185
	v_add_f32_e32 v46, v186, v178
	v_add_f32_e32 v47, v187, v179
	v_mul_f32_e32 v184, v44, v47
	v_mul_f32_e32 v185, v45, v47
	v_fma_f32 v186, v50, v46, -v184
	v_fma_f32 v187, v51, v46, v185
	v_add_f32_e32 v192, v186, v180
	v_add_f32_e32 v193, v187, v181
	v_mul_f32_e32 v184, v44, v193
	v_mul_f32_e32 v185, v45, v193
	v_fma_f32 v186, v50, v192, -v184
	v_fma_f32 v187, v51, v192, v185
	v_add_f32_e32 v46, v186, v182
	v_add_f32_e32 v47, v187, v183
	v_mov_b32_e32 v52, v47
	s_movk_i32 s14, 0x2100
	v_mfma_f32_16x16x32_bf16 v[56:59], v[28:31], v[8:11], 0
	s_barrier
	v_mfma_f32_16x16x32_bf16 v[60:63], v[28:31], v[4:7], 0
	s_nop 7
	ds_write2_b32 v53, v56, v60 offset1:16
	ds_write2_b32 v53, v57, v61 offset0:132 offset1:148
	ds_write2_b32 v54, v58, v62 offset0:8 offset1:24
	v_mfma_f32_16x16x32_bf16 v[64:67], v[28:31], v[20:23], 0
	s_mov_b32 s2, 0
	v_mfma_f32_16x16x32_bf16 v[68:71], v[28:31], v[16:19], 0
	ds_write2_b32 v54, v59, v63 offset0:140 offset1:156
	s_nop 6
	ds_write2_b32 v53, v64, v68 offset0:32 offset1:48
	ds_write2_b32 v53, v65, v69 offset0:164 offset1:180
	v_mfma_f32_16x16x32_bf16 v[72:75], v[28:31], v[32:35], 0
	v_mfma_f32_16x16x32_bf16 v[56:59], v[28:31], v[24:27], 0
	ds_write2_b32 v54, v66, v70 offset0:40 offset1:56
	ds_write2_b32 v54, v67, v71 offset0:172 offset1:188
	s_nop 5
	ds_write2_b32 v53, v72, v56 offset0:64 offset1:80
	ds_write2_b32 v53, v73, v57 offset0:196 offset1:212
	ds_write2_b32 v54, v74, v58 offset0:72 offset1:88
	ds_write2_b32 v54, v75, v59 offset0:204 offset1:220
	v_mfma_f32_16x16x32_bf16 v[60:63], v[28:31], v[40:43], 0
	v_mfma_f32_16x16x32_bf16 v[28:31], v[28:31], v[36:39], 0
	s_nop 7
	ds_write2_b32 v53, v60, v28 offset0:96 offset1:112
	ds_write2_b32 v53, v61, v29 offset0:228 offset1:244
	ds_write2_b32 v54, v62, v30 offset0:104 offset1:120
	ds_write2_b32 v54, v63, v31 offset0:236 offset1:252
	s_waitcnt lgkmcnt(0)
	s_barrier
; DI u16 f2bf(float x) { return (u16)(pk2(x, 0.f) & 0xffffu); }
; DI f32x4 mfma16(bf16x8 a, bf16x8 b, f32x4 c) { return __builtin_amdgcn_mfma_f32_16x16x32_bf16(a, b, c, 0, 0, 0); }
; template <bool OUT>
; DI void s5_item(int wv0, PP p, int item, unsigned char* smem) {
;     ...
;   for (int sub = 0; sub < 4; ++sub) {
;     const bf16x8 ua = uall[sub];
; #pragma unroll
;     for (int nt = 0; nt < 8; ++nt) {
;       const f32x4 a = mfma16(ua, bb[nt], f32x4{0.f, 0.f, 0.f, 0.f});
; #pragma unroll
;       for (int j = 0; j < 4; ++j) sBU[(4 * fq + j) * 132 + 16 * nt + fr] = a[j];
;     }
;     __syncthreads();
; #pragma unroll 4
;     for (int t = 0; t < 16; ++t) {
;       const float bur = sBU[t * 132 + lane], bui = sBU[t * 132 + 64 + lane];
;       const float nr = lbr * hr - lbi * hi + bur;
;       const float nim = lbr * hi + lbi * hr + bui;
;       hr = nr;
;       hi = nim;
;       if (OUT) {
;         sH[t * 136 + lane] = f2bf(hr);
;         sH[t * 136 + 64 + lane] = f2bf(hi);
;       }
;     }
.LBB0_443:
	v_mov_b32_e32 v117, v49
	v_add_u32_e32 v118, 1056, v49
	v_add_u32_e32 v119, 2112, v49
	v_add_u32_e32 v120, 3168, v49
	v_add_u32_e32 v121, 4224, v49
	v_add_u32_e32 v122, 5280, v49
	v_add_u32_e32 v123, 6336, v49
	v_add_u32_e32 v124, 7392, v49
	ds_read2st64_b32 v[152:153], v117 offset1:1
	ds_read2_b32 v[154:155], v117 offset0:132 offset1:196
	ds_read2st64_b32 v[156:157], v118 offset1:1
	ds_read2_b32 v[158:159], v118 offset0:132 offset1:196
	ds_read2st64_b32 v[160:161], v119 offset1:1
	ds_read2_b32 v[162:163], v119 offset0:132 offset1:196
	ds_read2st64_b32 v[164:165], v120 offset1:1
	ds_read2_b32 v[166:167], v120 offset0:132 offset1:196
	ds_read2st64_b32 v[168:169], v121 offset1:1
	ds_read2_b32 v[170:171], v121 offset0:132 offset1:196
	ds_read2st64_b32 v[172:173], v122 offset1:1
	ds_read2_b32 v[174:175], v122 offset0:132 offset1:196
	ds_read2st64_b32 v[176:177], v123 offset1:1
	ds_read2_b32 v[178:179], v123 offset0:132 offset1:196
	ds_read2st64_b32 v[180:181], v124 offset1:1
	ds_read2_b32 v[182:183], v124 offset0:132 offset1:196
	s_waitcnt lgkmcnt(0)
	v_mul_f32_e32 v184, v44, v47
	v_mul_f32_e32 v185, v45, v47
	v_fma_f32 v186, v50, v46, -v184
	v_fma_f32 v187, v51, v46, v185
	v_add_f32_e32 v192, v186, v152
	v_add_f32_e32 v193, v187, v153
	v_mul_f32_e32 v184, v44, v193
	v_mul_f32_e32 v185, v45, v193
	v_fma_f32 v186, v50, v192, -v184
	v_fma_f32 v187, v51, v192, v185
	v_add_f32_e32 v46, v186, v154
	v_add_f32_e32 v47, v187, v155
	v_mul_f32_e32 v184, v44, v47
	v_mul_f32_e32 v185, v45, v47
	v_fma_f32 v186, v50, v46, -v184
	v_fma_f32 v187, v51, v46, v185
	v_add_f32_e32 v192, v186, v156
	v_add_f32_e32 v193, v187, v157
	v_mul_f32_e32 v184, v44, v193
	v_mul_f32_e32 v185, v45, v193
	v_fma_f32 v186, v50, v192, -v184
	v_fma_f32 v187, v51, v192, v185
	v_add_f32_e32 v46, v186, v158
	v_add_f32_e32 v47, v187, v159
	v_mul_f32_e32 v184, v44, v47
	v_mul_f32_e32 v185, v45, v47
	v_fma_f32 v186, v50, v46, -v184
	v_fma_f32 v187, v51, v46, v185
	v_add_f32_e32 v192, v186, v160
	v_add_f32_e32 v193, v187, v161
	v_mul_f32_e32 v184, v44, v193
	v_mul_f32_e32 v185, v45, v193
	v_fma_f32 v186, v50, v192, -v184
	v_fma_f32 v187, v51, v192, v185
	v_add_f32_e32 v46, v186, v162
	v_add_f32_e32 v47, v187, v163
	v_mul_f32_e32 v184, v44, v47
	v_mul_f32_e32 v185, v45, v47
	v_fma_f32 v186, v50, v46, -v184
	v_fma_f32 v187, v51, v46, v185
	v_add_f32_e32 v192, v186, v164
	v_add_f32_e32 v193, v187, v165
	v_mul_f32_e32 v184, v44, v193
	v_mul_f32_e32 v185, v45, v193
	v_fma_f32 v186, v50, v192, -v184
	v_fma_f32 v187, v51, v192, v185
	v_add_f32_e32 v46, v186, v166
	v_add_f32_e32 v47, v187, v167
	v_mul_f32_e32 v184, v44, v47
	v_mul_f32_e32 v185, v45, v47
	v_fma_f32 v186, v50, v46, -v184
	v_fma_f32 v187, v51, v46, v185
	v_add_f32_e32 v192, v186, v168
	v_add_f32_e32 v193, v187, v169
	v_mul_f32_e32 v184, v44, v193
	v_mul_f32_e32 v185, v45, v193
	v_fma_f32 v186, v50, v192, -v184
	v_fma_f32 v187, v51, v192, v185
	v_add_f32_e32 v46, v186, v170
	v_add_f32_e32 v47, v187, v171
	v_mul_f32_e32 v184, v44, v47
	v_mul_f32_e32 v185, v45, v47
	v_fma_f32 v186, v50, v46, -v184
	v_fma_f32 v187, v51, v46, v185
	v_add_f32_e32 v192, v186, v172
	v_add_f32_e32 v193, v187, v173
	v_mul_f32_e32 v184, v44, v193
	v_mul_f32_e32 v185, v45, v193
	v_fma_f32 v186, v50, v192, -v184
	v_fma_f32 v187, v51, v192, v185
	v_add_f32_e32 v46, v186, v174
	v_add_f32_e32 v47, v187, v175
	v_mul_f32_e32 v184, v44, v47
	v_mul_f32_e32 v185, v45, v47
	v_fma_f32 v186, v50, v46, -v184
	v_fma_f32 v187, v51, v46, v185
	v_add_f32_e32 v192, v186, v176
	v_add_f32_e32 v193, v187, v177
	v_mul_f32_e32 v184, v44, v193
	v_mul_f32_e32 v185, v45, v193
	v_fma_f32 v186, v50, v192, -v184
	v_fma_f32 v187, v51, v192, v185
	v_add_f32_e32 v46, v186, v178
	v_add_f32_e32 v47, v187, v179
	v_mul_f32_e32 v184, v44, v47
	v_mul_f32_e32 v185, v45, v47
	v_fma_f32 v186, v50, v46, -v184
	v_fma_f32 v187, v51, v46, v185
	v_add_f32_e32 v192, v186, v180
	v_add_f32_e32 v193, v187, v181
	v_mul_f32_e32 v184, v44, v193
	v_mul_f32_e32 v185, v45, v193
	v_fma_f32 v186, v50, v192, -v184
	v_fma_f32 v187, v51, v192, v185
	v_add_f32_e32 v46, v186, v182
	v_add_f32_e32 v47, v187, v183
	s_movk_i32 s2, 0x2100
	v_mfma_f32_16x16x32_bf16 v[28:31], v[12:15], v[8:11], 0
	s_barrier
	v_mfma_f32_16x16x32_bf16 v[56:59], v[12:15], v[4:7], 0
	s_nop 7
	ds_write2_b32 v53, v28, v56 offset1:16
	ds_write2_b32 v53, v29, v57 offset0:132 offset1:148
	ds_write2_b32 v54, v30, v58 offset0:8 offset1:24
	v_mfma_f32_16x16x32_bf16 v[60:63], v[12:15], v[20:23], 0
	s_mov_b32 s2, 0
	v_mfma_f32_16x16x32_bf16 v[64:67], v[12:15], v[16:19], 0
	ds_write2_b32 v54, v31, v59 offset0:140 offset1:156
	s_nop 6
	ds_write2_b32 v53, v60, v64 offset0:32 offset1:48
	ds_write2_b32 v53, v61, v65 offset0:164 offset1:180
	v_mfma_f32_16x16x32_bf16 v[68:71], v[12:15], v[32:35], 0
	v_mfma_f32_16x16x32_bf16 v[28:31], v[12:15], v[24:27], 0
	ds_write2_b32 v54, v62, v66 offset0:40 offset1:56
	ds_write2_b32 v54, v63, v67 offset0:172 offset1:188
	s_nop 5
	ds_write2_b32 v53, v68, v28 offset0:64 offset1:80
	ds_write2_b32 v53, v69, v29 offset0:196 offset1:212
	ds_write2_b32 v54, v70, v30 offset0:72 offset1:88
	ds_write2_b32 v54, v71, v31 offset0:204 offset1:220
	v_mfma_f32_16x16x32_bf16 v[56:59], v[12:15], v[40:43], 0
	v_mfma_f32_16x16x32_bf16 v[12:15], v[12:15], v[36:39], 0
	s_nop 7
	ds_write2_b32 v53, v56, v12 offset0:96 offset1:112
	ds_write2_b32 v53, v57, v13 offset0:228 offset1:244
	ds_write2_b32 v54, v58, v14 offset0:104 offset1:120
	ds_write2_b32 v54, v59, v15 offset0:236 offset1:252
	s_waitcnt lgkmcnt(0)
	s_barrier
; DI u16 f2bf(float x) { return (u16)(pk2(x, 0.f) & 0xffffu); }
; DI f32x4 mfma16(bf16x8 a, bf16x8 b, f32x4 c) { return __builtin_amdgcn_mfma_f32_16x16x32_bf16(a, b, c, 0, 0, 0); }
; template <bool OUT>
; DI void s5_item(int wv0, PP p, int item, unsigned char* smem) {
;     ...
;   for (int sub = 0; sub < 4; ++sub) {
;     const bf16x8 ua = uall[sub];
; #pragma unroll
;     for (int nt = 0; nt < 8; ++nt) {
;       const f32x4 a = mfma16(ua, bb[nt], f32x4{0.f, 0.f, 0.f, 0.f});
; #pragma unroll
;       for (int j = 0; j < 4; ++j) sBU[(4 * fq + j) * 132 + 16 * nt + fr] = a[j];
;     }
;     __syncthreads();
; #pragma unroll 4
;     for (int t = 0; t < 16; ++t) {
;       const float bur = sBU[t * 132 + lane], bui = sBU[t * 132 + 64 + lane];
;       const float nr = lbr * hr - lbi * hi + bur;
;       const float nim = lbr * hi + lbi * hr + bui;
;       hr = nr;
;       hi = nim;
;       if (OUT) {
;         sH[t * 136 + lane] = f2bf(hr);
;         sH[t * 136 + 64 + lane] = f2bf(hi);
;       }
;     }
.LBB0_445:
	v_mov_b32_e32 v117, v49
	v_add_u32_e32 v118, 1056, v49
	v_add_u32_e32 v119, 2112, v49
	v_add_u32_e32 v120, 3168, v49
	v_add_u32_e32 v121, 4224, v49
	v_add_u32_e32 v122, 5280, v49
	v_add_u32_e32 v123, 6336, v49
	v_add_u32_e32 v124, 7392, v49
	ds_read2st64_b32 v[152:153], v117 offset1:1
	ds_read2_b32 v[154:155], v117 offset0:132 offset1:196
	ds_read2st64_b32 v[156:157], v118 offset1:1
	ds_read2_b32 v[158:159], v118 offset0:132 offset1:196
	ds_read2st64_b32 v[160:161], v119 offset1:1
	ds_read2_b32 v[162:163], v119 offset0:132 offset1:196
	ds_read2st64_b32 v[164:165], v120 offset1:1
	ds_read2_b32 v[166:167], v120 offset0:132 offset1:196
	ds_read2st64_b32 v[168:169], v121 offset1:1
	ds_read2_b32 v[170:171], v121 offset0:132 offset1:196
	ds_read2st64_b32 v[172:173], v122 offset1:1
	ds_read2_b32 v[174:175], v122 offset0:132 offset1:196
	ds_read2st64_b32 v[176:177], v123 offset1:1
	ds_read2_b32 v[178:179], v123 offset0:132 offset1:196
	ds_read2st64_b32 v[180:181], v124 offset1:1
	ds_read2_b32 v[182:183], v124 offset0:132 offset1:196
	s_waitcnt lgkmcnt(0)
	v_mul_f32_e32 v184, v44, v47
	v_mul_f32_e32 v185, v45, v47
	v_fma_f32 v186, v50, v46, -v184
	v_fma_f32 v187, v51, v46, v185
	v_add_f32_e32 v192, v186, v152
	v_add_f32_e32 v193, v187, v153
	v_mul_f32_e32 v184, v44, v193
	v_mul_f32_e32 v185, v45, v193
	v_fma_f32 v186, v50, v192, -v184
	v_fma_f32 v187, v51, v192, v185
	v_add_f32_e32 v46, v186, v154
	v_add_f32_e32 v47, v187, v155
	v_mul_f32_e32 v184, v44, v47
	v_mul_f32_e32 v185, v45, v47
	v_fma_f32 v186, v50, v46, -v184
	v_fma_f32 v187, v51, v46, v185
	v_add_f32_e32 v192, v186, v156
	v_add_f32_e32 v193, v187, v157
	v_mul_f32_e32 v184, v44, v193
	v_mul_f32_e32 v185, v45, v193
	v_fma_f32 v186, v50, v192, -v184
	v_fma_f32 v187, v51, v192, v185
	v_add_f32_e32 v46, v186, v158
	v_add_f32_e32 v47, v187, v159
	v_mul_f32_e32 v184, v44, v47
	v_mul_f32_e32 v185, v45, v47
	v_fma_f32 v186, v50, v46, -v184
	v_fma_f32 v187, v51, v46, v185
	v_add_f32_e32 v192, v186, v160
	v_add_f32_e32 v193, v187, v161
	v_mul_f32_e32 v184, v44, v193
	v_mul_f32_e32 v185, v45, v193
	v_fma_f32 v186, v50, v192, -v184
	v_fma_f32 v187, v51, v192, v185
	v_add_f32_e32 v46, v186, v162
	v_add_f32_e32 v47, v187, v163
	v_mul_f32_e32 v184, v44, v47
	v_mul_f32_e32 v185, v45, v47
	v_fma_f32 v186, v50, v46, -v184
	v_fma_f32 v187, v51, v46, v185
	v_add_f32_e32 v192, v186, v164
	v_add_f32_e32 v193, v187, v165
	v_mul_f32_e32 v184, v44, v193
	v_mul_f32_e32 v185, v45, v193
	v_fma_f32 v186, v50, v192, -v184
	v_fma_f32 v187, v51, v192, v185
	v_add_f32_e32 v46, v186, v166
	v_add_f32_e32 v47, v187, v167
	v_mul_f32_e32 v184, v44, v47
	v_mul_f32_e32 v185, v45, v47
	v_fma_f32 v186, v50, v46, -v184
	v_fma_f32 v187, v51, v46, v185
	v_add_f32_e32 v192, v186, v168
	v_add_f32_e32 v193, v187, v169
	v_mul_f32_e32 v184, v44, v193
	v_mul_f32_e32 v185, v45, v193
	v_fma_f32 v186, v50, v192, -v184
	v_fma_f32 v187, v51, v192, v185
	v_add_f32_e32 v46, v186, v170
	v_add_f32_e32 v47, v187, v171
	v_mul_f32_e32 v184, v44, v47
	v_mul_f32_e32 v185, v45, v47
	v_fma_f32 v186, v50, v46, -v184
	v_fma_f32 v187, v51, v46, v185
	v_add_f32_e32 v192, v186, v172
	v_add_f32_e32 v193, v187, v173
	v_mul_f32_e32 v184, v44, v193
	v_mul_f32_e32 v185, v45, v193
	v_fma_f32 v186, v50, v192, -v184
	v_fma_f32 v187, v51, v192, v185
	v_add_f32_e32 v46, v186, v174
	v_add_f32_e32 v47, v187, v175
	v_mul_f32_e32 v184, v44, v47
	v_mul_f32_e32 v185, v45, v47
	v_fma_f32 v186, v50, v46, -v184
	v_fma_f32 v187, v51, v46, v185
	v_add_f32_e32 v192, v186, v176
	v_add_f32_e32 v193, v187, v177
	v_mul_f32_e32 v184, v44, v193
	v_mul_f32_e32 v185, v45, v193
	v_fma_f32 v186, v50, v192, -v184
	v_fma_f32 v187, v51, v192, v185
	v_add_f32_e32 v46, v186, v178
	v_add_f32_e32 v47, v187, v179
	v_mul_f32_e32 v184, v44, v47
	v_mul_f32_e32 v185, v45, v47
	v_fma_f32 v186, v50, v46, -v184
	v_fma_f32 v187, v51, v46, v185
	v_add_f32_e32 v192, v186, v180
	v_add_f32_e32 v193, v187, v181
	v_mul_f32_e32 v184, v44, v193
	v_mul_f32_e32 v185, v45, v193
	v_fma_f32 v186, v50, v192, -v184
	v_fma_f32 v187, v51, v192, v185
	v_add_f32_e32 v46, v186, v182
	v_add_f32_e32 v47, v187, v183
	s_movk_i32 s2, 0x2100
	v_mfma_f32_16x16x32_bf16 v[8:11], v[0:3], v[8:11], 0
	s_barrier
	v_mfma_f32_16x16x32_bf16 v[4:7], v[0:3], v[4:7], 0
	s_nop 7
	ds_write2_b32 v53, v8, v4 offset1:16
	ds_write2_b32 v53, v9, v5 offset0:132 offset1:148
	ds_write2_b32 v54, v10, v6 offset0:8 offset1:24
	v_mfma_f32_16x16x32_bf16 v[12:15], v[0:3], v[20:23], 0
	s_mov_b32 s2, 0
	v_mfma_f32_16x16x32_bf16 v[16:19], v[0:3], v[16:19], 0
	ds_write2_b32 v54, v11, v7 offset0:140 offset1:156
	s_nop 6
	ds_write2_b32 v53, v12, v16 offset0:32 offset1:48
	ds_write2_b32 v53, v13, v17 offset0:164 offset1:180
	v_mfma_f32_16x16x32_bf16 v[20:23], v[0:3], v[32:35], 0
	v_mfma_f32_16x16x32_bf16 v[4:7], v[0:3], v[24:27], 0
	ds_write2_b32 v54, v14, v18 offset0:40 offset1:56
	ds_write2_b32 v54, v15, v19 offset0:172 offset1:188
	s_nop 5
	ds_write2_b32 v53, v20, v4 offset0:64 offset1:80
	ds_write2_b32 v53, v21, v5 offset0:196 offset1:212
	ds_write2_b32 v54, v22, v6 offset0:72 offset1:88
	ds_write2_b32 v54, v23, v7 offset0:204 offset1:220
	v_mfma_f32_16x16x32_bf16 v[8:11], v[0:3], v[40:43], 0
	v_mfma_f32_16x16x32_bf16 v[0:3], v[0:3], v[36:39], 0
	s_nop 7
	ds_write2_b32 v53, v8, v0 offset0:96 offset1:112
	ds_write2_b32 v53, v9, v1 offset0:228 offset1:244
	ds_write2_b32 v54, v10, v2 offset0:104 offset1:120
	ds_write2_b32 v54, v11, v3 offset0:236 offset1:252
	s_waitcnt lgkmcnt(0)
	s_barrier
; DI u16 f2bf(float x) { return (u16)(pk2(x, 0.f) & 0xffffu); }
; template <bool OUT>
; DI void s5_item(int wv0, PP p, int item, unsigned char* smem) {
;     ...
; #pragma unroll 4
;     for (int t = 0; t < 16; ++t) {
;       const float bur = sBU[t * 132 + lane], bui = sBU[t * 132 + 64 + lane];
;       const float nr = lbr * hr - lbi * hi + bur;
;       const float nim = lbr * hi + lbi * hr + bui;
;       hr = nr;
;       hi = nim;
;       if (OUT) {
;         sH[t * 136 + lane] = f2bf(hr);
;         sH[t * 136 + 64 + lane] = f2bf(hi);
;       }
;     }
;     ...
;   if (!OUT) *HL = make_float2(hr, hi);
;   __syncthreads();
.LBB0_447:
	v_mov_b32_e32 v117, v49
	v_add_u32_e32 v118, 1056, v49
	v_add_u32_e32 v119, 2112, v49
	v_add_u32_e32 v120, 3168, v49
	v_add_u32_e32 v121, 4224, v49
	v_add_u32_e32 v122, 5280, v49
	v_add_u32_e32 v123, 6336, v49
	v_add_u32_e32 v124, 7392, v49
	ds_read2st64_b32 v[152:153], v117 offset1:1
	ds_read2_b32 v[154:155], v117 offset0:132 offset1:196
	ds_read2st64_b32 v[156:157], v118 offset1:1
	ds_read2_b32 v[158:159], v118 offset0:132 offset1:196
	ds_read2st64_b32 v[160:161], v119 offset1:1
	ds_read2_b32 v[162:163], v119 offset0:132 offset1:196
	ds_read2st64_b32 v[164:165], v120 offset1:1
	ds_read2_b32 v[166:167], v120 offset0:132 offset1:196
	ds_read2st64_b32 v[168:169], v121 offset1:1
	ds_read2_b32 v[170:171], v121 offset0:132 offset1:196
	ds_read2st64_b32 v[172:173], v122 offset1:1
	ds_read2_b32 v[174:175], v122 offset0:132 offset1:196
	ds_read2st64_b32 v[176:177], v123 offset1:1
	ds_read2_b32 v[178:179], v123 offset0:132 offset1:196
	ds_read2st64_b32 v[180:181], v124 offset1:1
	ds_read2_b32 v[182:183], v124 offset0:132 offset1:196
	s_waitcnt lgkmcnt(0)
	v_mul_f32_e32 v184, v44, v47
	v_mul_f32_e32 v185, v45, v47
	v_fma_f32 v186, v50, v46, -v184
	v_fma_f32 v187, v51, v46, v185
	v_add_f32_e32 v192, v186, v152
	v_add_f32_e32 v193, v187, v153
	v_mul_f32_e32 v184, v44, v193
	v_mul_f32_e32 v185, v45, v193
	v_fma_f32 v186, v50, v192, -v184
	v_fma_f32 v187, v51, v192, v185
	v_add_f32_e32 v46, v186, v154
	v_add_f32_e32 v47, v187, v155
	v_mul_f32_e32 v184, v44, v47
	v_mul_f32_e32 v185, v45, v47
	v_fma_f32 v186, v50, v46, -v184
	v_fma_f32 v187, v51, v46, v185
	v_add_f32_e32 v192, v186, v156
	v_add_f32_e32 v193, v187, v157
	v_mul_f32_e32 v184, v44, v193
	v_mul_f32_e32 v185, v45, v193
	v_fma_f32 v186, v50, v192, -v184
	v_fma_f32 v187, v51, v192, v185
	v_add_f32_e32 v46, v186, v158
	v_add_f32_e32 v47, v187, v159
	v_mul_f32_e32 v184, v44, v47
	v_mul_f32_e32 v185, v45, v47
	v_fma_f32 v186, v50, v46, -v184
	v_fma_f32 v187, v51, v46, v185
	v_add_f32_e32 v192, v186, v160
	v_add_f32_e32 v193, v187, v161
	v_mul_f32_e32 v184, v44, v193
	v_mul_f32_e32 v185, v45, v193
	v_fma_f32 v186, v50, v192, -v184
	v_fma_f32 v187, v51, v192, v185
	v_add_f32_e32 v46, v186, v162
	v_add_f32_e32 v47, v187, v163
	v_mul_f32_e32 v184, v44, v47
	v_mul_f32_e32 v185, v45, v47
	v_fma_f32 v186, v50, v46, -v184
	v_fma_f32 v187, v51, v46, v185
	v_add_f32_e32 v192, v186, v164
	v_add_f32_e32 v193, v187, v165
	v_mul_f32_e32 v184, v44, v193
	v_mul_f32_e32 v185, v45, v193
	v_fma_f32 v186, v50, v192, -v184
	v_fma_f32 v187, v51, v192, v185
	v_add_f32_e32 v46, v186, v166
	v_add_f32_e32 v47, v187, v167
	v_mul_f32_e32 v184, v44, v47
	v_mul_f32_e32 v185, v45, v47
	v_fma_f32 v186, v50, v46, -v184
	v_fma_f32 v187, v51, v46, v185
	v_add_f32_e32 v192, v186, v168
	v_add_f32_e32 v193, v187, v169
	v_mul_f32_e32 v184, v44, v193
	v_mul_f32_e32 v185, v45, v193
	v_fma_f32 v186, v50, v192, -v184
	v_fma_f32 v187, v51, v192, v185
	v_add_f32_e32 v46, v186, v170
	v_add_f32_e32 v47, v187, v171
	v_mul_f32_e32 v184, v44, v47
	v_mul_f32_e32 v185, v45, v47
	v_fma_f32 v186, v50, v46, -v184
	v_fma_f32 v187, v51, v46, v185
	v_add_f32_e32 v192, v186, v172
	v_add_f32_e32 v193, v187, v173
	v_mul_f32_e32 v184, v44, v193
	v_mul_f32_e32 v185, v45, v193
	v_fma_f32 v186, v50, v192, -v184
	v_fma_f32 v187, v51, v192, v185
	v_add_f32_e32 v46, v186, v174
	v_add_f32_e32 v47, v187, v175
	v_mul_f32_e32 v184, v44, v47
	v_mul_f32_e32 v185, v45, v47
	v_fma_f32 v186, v50, v46, -v184
	v_fma_f32 v187, v51, v46, v185
	v_add_f32_e32 v192, v186, v176
	v_add_f32_e32 v193, v187, v177
	v_mul_f32_e32 v184, v44, v193
	v_mul_f32_e32 v185, v45, v193
	v_fma_f32 v186, v50, v192, -v184
	v_fma_f32 v187, v51, v192, v185
	v_add_f32_e32 v46, v186, v178
	v_add_f32_e32 v47, v187, v179
	v_mul_f32_e32 v184, v44, v47
	v_mul_f32_e32 v185, v45, v47
	v_fma_f32 v186, v50, v46, -v184
	v_fma_f32 v187, v51, v46, v185
	v_add_f32_e32 v192, v186, v180
	v_add_f32_e32 v193, v187, v181
	v_mul_f32_e32 v184, v44, v193
	v_mul_f32_e32 v185, v45, v193
	v_fma_f32 v186, v50, v192, -v184
	v_fma_f32 v187, v51, v192, v185
	v_add_f32_e32 v46, v186, v182
	v_add_f32_e32 v47, v187, v183
	s_movk_i32 s2, 0x2100
	s_lshl_b32 s2, s66, 7
	s_add_i32 s14, s67, s2
	s_lshl_b64 s[2:3], s[14:15], 14
	s_add_u32 s2, s42, s2
	s_addc_u32 s3, s43, s3
	s_lshl_b32 s14, s65, 9
	s_add_u32 s2, s2, s14
	s_addc_u32 s3, s3, 0
	v_mov_b32_e32 v49, v129
	v_lshl_add_u64 v[0:1], s[2:3], 0, v[48:49]
	v_add_co_u32_e32 v0, vcc, 0x2bd4000, v0
	s_nop 1
	v_addc_co_u32_e32 v1, vcc, 0, v1, vcc
	s_barrier
	global_store_dwordx2 v[0:1], v[46:47], off offset:256
	s_barrier
	s_mov_b64 s[2:3], 0
